# attention original tile body: xor-16/xor-32 row-max exchange via v_permlane16_swap / v_permlane32_swap on two copies instead of four ds_bpermute round trips (strategy 7); on top of v053
# speedup vs baseline: 1.0026x; 1.0020x over previous
.LBB0_878:
	s_nop 3
	s_xor_b64 s[4:5], s[74:75], -1
	s_mov_b64 s[34:35], -1
	v_max_f32_e32 v104, v230, v230
	v_mov_b32_e32 v105, v104
	s_nop 1
	v_permlane16_swap_b32_e32 v104, v105
	v_max_f32_e32 v231, v104, v105
	v_mov_b32_e32 v232, v231
	s_nop 1
	v_permlane32_swap_b32_e32 v231, v232
	s_andn2_b64 vcc, exec, s[4:5]
	s_cbranch_vccnz .LBB0_880
	v_sub_f32_e32 v104, v142, v84
	v_sub_f32_e32 v105, v143, v85
	v_sub_f32_e32 v106, v142, v86
	v_sub_f32_e32 v107, v143, v87
	v_add_f32_e32 v104, v104, v100
	v_add_f32_e32 v105, v105, v101
	v_add_f32_e32 v106, v106, v102
	v_add_f32_e32 v107, v107, v103
	v_max3_f32 v108, v104, s86, v105
	v_max3_f32 v110, v108, v106, v107
	v_sub_f32_e32 v108, v142, v76
	v_sub_f32_e32 v109, v143, v77
	s_mov_b64 s[34:35], 0
	v_add_f32_e32 v108, v108, v96
	v_add_f32_e32 v109, v109, v97
	v_max3_f32 v112, v110, v108, v109
	v_sub_f32_e32 v110, v142, v78
	v_sub_f32_e32 v111, v143, v79
	v_add_f32_e32 v110, v110, v98
	v_add_f32_e32 v111, v111, v99
	v_max3_f32 v114, v112, v110, v111
	v_sub_f32_e32 v112, v142, v80
	v_sub_f32_e32 v113, v143, v81
	v_add_f32_e32 v112, v112, v92
	v_add_f32_e32 v113, v113, v93
	v_max3_f32 v116, v114, v112, v113
	v_sub_f32_e32 v114, v142, v82
	v_sub_f32_e32 v115, v143, v83
	v_add_f32_e32 v114, v114, v94
	v_add_f32_e32 v115, v115, v95
	v_max3_f32 v118, v116, v114, v115
	v_sub_f32_e32 v116, v142, v72
	v_sub_f32_e32 v117, v143, v73
	v_add_f32_e32 v116, v116, v88
	v_add_f32_e32 v117, v117, v89
	v_max3_f32 v202, v118, v116, v117
	v_sub_f32_e32 v118, v142, v74
	v_sub_f32_e32 v119, v143, v75
	v_add_f32_e32 v118, v118, v90
	v_add_f32_e32 v119, v119, v91
	v_max3_f32 v230, v202, v118, v119

.LBB0_882:
	s_waitcnt lgkmcnt(0)
	v_max3_f32 v89, v227, v231, v232
	v_sub_f32_e32 v72, v227, v89
	v_exp_f32_e32 v88, v72
	v_sub_f32_e32 v72, v160, v89
	v_exp_f32_e32 v72, v72
	v_sub_f32_e32 v74, v161, v89
	v_exp_f32_e32 v74, v74
	v_sub_f32_e32 v75, v162, v89
	v_sub_f32_e32 v76, v163, v89
	v_exp_f32_e32 v75, v75
	v_exp_f32_e32 v77, v76
	v_sub_f32_e32 v76, v164, v89
	v_exp_f32_e32 v78, v76
	v_sub_f32_e32 v76, v165, v89
	v_add_f32_e32 v73, 0, v72
	v_exp_f32_e32 v79, v76
	v_sub_f32_e32 v76, v168, v89
	v_add_f32_e32 v73, v74, v73
	v_exp_f32_e32 v80, v76
	v_sub_f32_e32 v76, v169, v89
	v_add_f32_e32 v73, v75, v73
	v_exp_f32_e32 v81, v76
	v_add_f32_e32 v73, v77, v73
	v_cvt_pk_bf16_f32 v76, v72, v74
	v_sub_f32_e32 v72, v166, v89
	v_add_f32_e32 v73, v78, v73
	v_exp_f32_e32 v72, v72
	v_sub_f32_e32 v74, v167, v89
	v_add_f32_e32 v73, v79, v73
	v_cvt_pk_bf16_f32 v77, v75, v77
	v_exp_f32_e32 v74, v74
	v_sub_f32_e32 v75, v170, v89
	v_add_f32_e32 v73, v80, v73
	v_cvt_pk_bf16_f32 v78, v78, v79
	v_cvt_pk_bf16_f32 v79, v80, v81
	v_exp_f32_e32 v75, v75
	v_sub_f32_e32 v80, v171, v89
	v_add_f32_e32 v73, v81, v73
	v_exp_f32_e32 v80, v80
	v_sub_f32_e32 v81, v172, v89
	v_add_f32_e32 v73, v72, v73
	v_exp_f32_e32 v81, v81
	v_sub_f32_e32 v82, v173, v89
	v_add_f32_e32 v73, v74, v73
	v_exp_f32_e32 v82, v82
	v_sub_f32_e32 v83, v174, v89
	v_add_f32_e32 v73, v75, v73
	v_exp_f32_e32 v83, v83
	v_sub_f32_e32 v84, v175, v89
	v_add_f32_e32 v73, v80, v73
	v_exp_f32_e32 v84, v84
	v_add_f32_e32 v73, v81, v73
	v_add_f32_e32 v73, v82, v73
	v_add_f32_e32 v73, v83, v73
	v_add_f32_e32 v91, v84, v73
	v_cvt_pk_bf16_f32 v73, v75, v80
	v_max_f32_e32 v80, v230, v230
	v_cvt_pk_bf16_f32 v72, v72, v74
	v_cvt_pk_bf16_f32 v74, v81, v82
	v_mov_b32_e32 v81, v80
	v_cvt_pk_bf16_f32 v75, v83, v84
	s_nop 1
	v_permlane16_swap_b32_e32 v80, v81
	v_max_f32_e32 v80, v81, v80
	v_mov_b32_e32 v81, v80
	v_fmac_f32_e32 v91, v225, v88
	v_mul_f32_e32 v54, v54, v88
	v_mul_f32_e32 v55, v55, v88
	v_mul_f32_e32 v52, v52, v88
	v_mul_f32_e32 v53, v53, v88
	v_mul_f32_e32 v46, v46, v88
	v_mul_f32_e32 v47, v47, v88
	v_permlane32_swap_b32_e32 v80, v81
	v_max3_f32 v92, v226, v80, v81
	v_sub_f32_e32 v80, v226, v92
	v_exp_f32_e32 v90, v80
	v_sub_f32_e32 v80, v104, v92
	v_exp_f32_e32 v80, v80
	v_sub_f32_e32 v82, v105, v92
	v_exp_f32_e32 v82, v82
	v_sub_f32_e32 v83, v106, v92
	v_sub_f32_e32 v84, v107, v92
	v_exp_f32_e32 v83, v83
	v_exp_f32_e32 v85, v84
	v_sub_f32_e32 v84, v108, v92
	v_exp_f32_e32 v86, v84
	v_sub_f32_e32 v84, v109, v92
	v_add_f32_e32 v81, 0, v80
	v_exp_f32_e32 v87, v84
	v_sub_f32_e32 v84, v110, v92
	v_add_f32_e32 v81, v82, v81
	v_exp_f32_e32 v93, v84
	v_sub_f32_e32 v84, v111, v92
	v_add_f32_e32 v81, v83, v81
	v_exp_f32_e32 v94, v84
	v_add_f32_e32 v81, v85, v81
	v_cvt_pk_bf16_f32 v84, v80, v82
	v_sub_f32_e32 v80, v112, v92
	v_add_f32_e32 v81, v86, v81
	v_exp_f32_e32 v80, v80
	v_sub_f32_e32 v82, v113, v92
	v_add_f32_e32 v81, v87, v81
	v_cvt_pk_bf16_f32 v85, v83, v85
	v_exp_f32_e32 v82, v82
	v_sub_f32_e32 v83, v114, v92
	v_add_f32_e32 v81, v93, v81
	v_cvt_pk_bf16_f32 v86, v86, v87
	v_cvt_pk_bf16_f32 v87, v93, v94
	v_exp_f32_e32 v83, v83
	v_sub_f32_e32 v93, v115, v92
	v_add_f32_e32 v81, v94, v81
	v_exp_f32_e32 v94, v93
	v_sub_f32_e32 v93, v116, v92
	v_add_f32_e32 v81, v80, v81
	v_exp_f32_e32 v95, v93
	v_sub_f32_e32 v93, v117, v92
	v_add_f32_e32 v81, v82, v81
	v_exp_f32_e32 v96, v93
	v_sub_f32_e32 v93, v118, v92
	v_add_f32_e32 v81, v83, v81
	v_exp_f32_e32 v97, v93
	v_sub_f32_e32 v93, v119, v92
	v_add_f32_e32 v81, v94, v81
	v_exp_f32_e32 v98, v93
	v_add_f32_e32 v81, v95, v81
	v_add_f32_e32 v81, v96, v81
	v_add_f32_e32 v81, v97, v81
	v_add_f32_e32 v93, v98, v81
	v_cvt_pk_bf16_f32 v80, v80, v82
	v_cvt_pk_bf16_f32 v81, v83, v94
	v_cvt_pk_bf16_f32 v82, v95, v96
	v_cvt_pk_bf16_f32 v83, v97, v98
	ds_read_b128 v[94:97], v222 offset:9216
	v_mul_f32_e32 v38, v38, v90
	v_mul_f32_e32 v39, v39, v90
	v_mul_f32_e32 v36, v36, v90
	v_mul_f32_e32 v37, v37, v90
	s_waitcnt lgkmcnt(0)
	v_mfma_f32_16x16x32_bf16 v[52:55], v[94:97], v[76:79], v[52:55]
	v_mul_f32_e64 v44, v44, v88
	v_mul_f32_e64 v45, v45, v88
	v_mul_f32_e32 v30, v30, v90
	v_mul_f32_e32 v31, v31, v90
	v_mul_f32_e32 v28, v28, v90
	v_mul_f32_e32 v29, v29, v90
	v_mfma_f32_16x16x32_bf16 v[36:39], v[94:97], v[84:87], v[36:39]
	ds_read_b128 v[94:97], v222 offset:9280
	v_mul_f32_e32 v42, v42, v88
	v_mul_f32_e32 v43, v43, v88
	v_mul_f32_e32 v40, v40, v88
	v_mul_f32_e32 v41, v41, v88
	s_waitcnt lgkmcnt(0)
	v_mfma_f32_16x16x32_bf16 v[52:55], v[94:97], v[72:75], v[52:55]
	v_mul_f32_e64 v18, v18, v90
	v_mul_f32_e64 v19, v19, v90
	v_mul_f32_e32 v16, v16, v90
	v_mul_f32_e32 v17, v17, v90
	v_mul_f32_e32 v50, v50, v88
	v_mul_f32_e32 v51, v51, v88
	v_mfma_f32_16x16x32_bf16 v[36:39], v[94:97], v[80:83], v[36:39]
	ds_read_b128 v[94:97], v222 offset:11520
	v_mul_f32_e32 v48, v48, v88
	v_mul_f32_e32 v49, v49, v88
	v_mul_f32_e32 v34, v34, v90
	v_mul_f32_e32 v35, v35, v90
	s_waitcnt lgkmcnt(0)
	v_mfma_f32_16x16x32_bf16 v[44:47], v[94:97], v[76:79], v[44:47]
	v_mul_f32_e64 v32, v32, v90
	v_mul_f32_e64 v33, v33, v90
	v_fmac_f32_e32 v93, v224, v90
	v_mov_b32_e32 v226, v92
	v_mfma_f32_16x16x32_bf16 v[28:31], v[94:97], v[84:87], v[28:31]
	ds_read_b128 v[94:97], v222 offset:11584
	v_mov_b32_e32 v227, v89
	v_mov_b32_e32 v224, v93
	s_waitcnt lgkmcnt(0)
	v_mfma_f32_16x16x32_bf16 v[44:47], v[94:97], v[72:75], v[44:47]
	v_mov_b32_e32 v225, v91
	v_mfma_f32_16x16x32_bf16 v[28:31], v[94:97], v[80:83], v[28:31]
	ds_read_b128 v[94:97], v222 offset:13824
	s_waitcnt lgkmcnt(0)
	v_mfma_f32_16x16x32_bf16 v[40:43], v[94:97], v[76:79], v[40:43]
	v_mfma_f32_16x16x32_bf16 v[16:19], v[94:97], v[84:87], v[16:19]
	ds_read_b128 v[94:97], v222 offset:13888
	s_waitcnt lgkmcnt(0)
	v_mfma_f32_16x16x32_bf16 v[40:43], v[94:97], v[72:75], v[40:43]
	v_mfma_f32_16x16x32_bf16 v[16:19], v[94:97], v[80:83], v[16:19]
	ds_read_b128 v[94:97], v223 offset:9216
	s_waitcnt lgkmcnt(0)
	v_mfma_f32_16x16x32_bf16 v[48:51], v[94:97], v[76:79], v[48:51]
	ds_read_b128 v[76:79], v223 offset:9280
	v_mfma_f32_16x16x32_bf16 v[32:35], v[94:97], v[84:87], v[32:35]
	s_waitcnt lgkmcnt(0)
	v_mfma_f32_16x16x32_bf16 v[48:51], v[76:79], v[72:75], v[48:51]
	v_mfma_f32_16x16x32_bf16 v[32:35], v[76:79], v[80:83], v[32:35]
